# mem_unit (P2,P6): removed the vmcnt(0) drain between the first K/V tile DMA and tiles 1-2 (q fragments and tile 0 now retire at the loop's counted vmcnt(8))
# speedup vs baseline: 1.0033x; 1.0033x over previous
.LBB0_537:
	s_lshr_b32 s9, s33, 4
	s_and_b64 s[16:17], s[6:7], exec
	s_cselect_b32 s9, s33, s9
	s_lshl_b32 s9, s9, 7
	s_and_b32 s9, s9, 0x180
	s_lshl_b32 s70, s9, 1
	s_add_u32 s12, s12, s70
	s_addc_u32 s13, s13, 0
	v_readlane_b32 s9, v254, 50
	s_add_u32 s9, s9, s14
	v_readlane_b32 s14, v254, 48
	s_addc_u32 s14, s14, s15
	s_add_u32 s9, s9, s70
	v_mov_b64_e32 v[2:3], s[76:77]
	s_addc_u32 s16, s14, 0
	s_waitcnt vmcnt(0)
	v_mad_u64_u32 v[144:145], s[14:15], v146, s20, v[2:3]
	v_mov_b32_e32 v0, v145
	v_mad_u64_u32 v[2:3], s[14:15], v147, s20, v[0:1]
	v_mov_b32_e32 v145, v2
	v_lshl_add_u64 v[2:3], v[144:145], 0, s[70:71]
	v_mov_b32_e32 v191, v1
	v_lshl_add_u64 v[2:3], v[2:3], 0, v[190:191]
	s_mov_b64 s[14:15], 0x1000
	v_lshl_add_u64 v[4:5], v[2:3], 0, s[14:15]
	v_add_co_u32_e32 v2, vcc, s21, v2
	v_mov_b32_e32 v0, v180
	s_nop 0
	v_addc_co_u32_e32 v3, vcc, 0, v3, vcc
	global_load_dwordx4 v[140:143], v[2:3], off
	global_load_dwordx4 v[136:139], v[4:5], off offset:32
	global_load_dwordx4 v[132:135], v[4:5], off offset:64
	global_load_dwordx4 v[128:131], v[4:5], off offset:96
	global_load_dwordx4 v[124:127], v[4:5], off offset:128
	global_load_dwordx4 v[120:123], v[4:5], off offset:160
	global_load_dwordx4 v[116:119], v[4:5], off offset:192
	global_load_dwordx4 v[112:115], v[4:5], off offset:224
	s_add_u32 s17, s12, 0x400
	s_addc_u32 s18, s13, 0
	s_and_b64 s[14:15], s[6:7], exec
	s_cselect_b32 s14, s9, s17
	v_readfirstlane_b32 s9, v0
	s_cselect_b32 s15, s16, s18
	s_lshl_b32 s9, s9, 4
	s_and_b32 s9, s9, 0xfffffc00
	v_and_b32_e32 v2, 63, v0
	s_ashr_i32 s16, s9, 8
	v_lshlrev_b32_e32 v12, 4, v2
	s_and_b32 s17, s16, 0xfffff0
	s_lshr_b32 s16, s16, 1
	v_lshlrev_b32_e32 v13, 3, v2
	v_bfe_u32 v2, v0, 2, 2
	v_lshrrev_b32_e32 v14, 1, v0
	v_or_b32_e32 v4, s9, v12
	s_and_b32 s16, s16, 4
	v_and_or_b32 v8, v14, 8, v2
	v_ashrrev_i32_e32 v2, 8, v4
	s_or_b32 s16, s17, s16
	v_xor_b32_e32 v5, v2, v0
	v_or_b32_e32 v6, s16, v8
	s_add_i32 s16, s9, 0x2000
	v_mul_hi_i32_i24_e32 v3, s8, v2
	v_mul_i32_i24_e32 v2, s8, v2
	v_lshlrev_b32_e32 v5, 3, v5
	v_lshrrev_b32_e32 v4, 4, v4
	v_or_b32_e32 v9, s16, v12
	s_ashr_i32 s16, s16, 8
	v_and_b32_e32 v15, 24, v13
	v_and_or_b32 v2, v5, s22, v2
	v_and_b32_e32 v4, 0x60, v4
	v_mul_hi_i32_i24_e32 v5, s8, v6
	v_mul_i32_i24_e32 v6, s8, v6
	s_and_b32 s17, s16, 0xfffff0
	s_lshr_b32 s16, s16, 1
	v_or3_b32 v4, v4, v15, v6
	v_ashrrev_i32_e32 v6, 8, v9
	s_and_b32 s16, s16, 4
	v_xor_b32_e32 v10, v6, v0
	s_or_b32 s16, s17, s16
	v_mul_hi_i32_i24_e32 v7, s8, v6
	v_mul_i32_i24_e32 v6, s8, v6
	v_lshlrev_b32_e32 v10, 3, v10
	v_or_b32_e32 v8, s16, v8
	v_lshrrev_b32_e32 v9, 4, v9
	v_and_or_b32 v6, v10, s22, v6
	v_and_b32_e32 v10, 0x60, v9
	v_mul_hi_i32_i24_e32 v9, s8, v8
	v_mul_i32_i24_e32 v8, s8, v8
	v_or3_b32 v8, v10, v15, v8
	s_add_i32 s16, s9, 0
	v_lshlrev_b64 v[4:5], 1, v[4:5]
	v_lshl_add_u64 v[10:11], s[14:15], 0, v[4:5]
	s_mov_b32 m0, s16
	v_lshlrev_b64 v[8:9], 1, v[8:9]
	global_load_lds_dwordx4 v[10:11], off
	v_lshl_add_u64 v[10:11], s[14:15], 0, v[8:9]
	s_add_i32 m0, s16, 0x2000
	v_lshlrev_b64 v[2:3], 1, v[2:3]
	global_load_lds_dwordx4 v[10:11], off
	v_lshl_add_u64 v[10:11], s[12:13], 0, v[2:3]
	s_add_i32 m0, s16, 0x4000
	s_lshl_b32 s17, s8, 7
	global_load_lds_dwordx4 v[10:11], off
	s_add_i32 m0, s16, 0x6000
	s_add_u32 s8, s12, s17
	v_lshlrev_b64 v[6:7], 1, v[6:7]
	s_addc_u32 s9, s13, 0
	v_lshl_add_u64 v[10:11], s[12:13], 0, v[6:7]
	s_add_u32 s12, s14, s17
	s_addc_u32 s13, s15, 0
	global_load_lds_dwordx4 v[10:11], off
	s_add_i32 m0, s16, 0x8000
	v_lshl_add_u64 v[10:11], s[12:13], 0, v[4:5]
	global_load_lds_dwordx4 v[10:11], off
	v_lshl_add_u64 v[10:11], s[12:13], 0, v[8:9]
	s_add_i32 m0, s16, 0xa000
	v_and_b32_e32 v150, 16, v14
	global_load_lds_dwordx4 v[10:11], off
	v_lshl_add_u64 v[10:11], s[8:9], 0, v[2:3]
	s_add_i32 m0, s16, 0xc000
	s_nop 0
	global_load_lds_dwordx4 v[10:11], off
	s_add_i32 m0, s16, 0xe000
	v_lshl_add_u64 v[10:11], s[8:9], 0, v[6:7]
	s_add_u32 s8, s8, s17
	s_addc_u32 s9, s9, 0
	s_add_u32 s12, s12, s17
	s_addc_u32 s13, s13, 0
	global_load_lds_dwordx4 v[10:11], off
	s_add_i32 m0, s16, 0x10000
	v_lshl_add_u64 v[10:11], s[12:13], 0, v[4:5]
	global_load_lds_dwordx4 v[10:11], off
	v_lshl_add_u64 v[10:11], s[12:13], 0, v[8:9]
	s_add_i32 m0, s16, 0x12000
	s_nop 0
	global_load_lds_dwordx4 v[10:11], off
	v_lshl_add_u64 v[10:11], s[8:9], 0, v[2:3]
	s_add_i32 m0, s16, 0x14000
	s_nop 0
	global_load_lds_dwordx4 v[10:11], off
	s_add_i32 m0, s16, 0x16000
	v_lshl_add_u64 v[10:11], s[8:9], 0, v[6:7]
	s_add_u32 s8, s8, s17
	s_addc_u32 s9, s9, 0
	s_add_u32 s12, s12, s17
	global_load_lds_dwordx4 v[10:11], off
	s_addc_u32 s13, s13, 0
	s_add_i32 m0, s16, 0x18000
	s_add_i32 s14, s16, 0x1a000
	s_waitcnt vmcnt(8)
	s_barrier
	v_lshl_add_u64 v[4:5], s[12:13], 0, v[4:5]
	s_add_i32 s15, s16, 0x1c000
	global_load_lds_dwordx4 v[4:5], off
	v_lshl_add_u64 v[4:5], s[12:13], 0, v[8:9]
	s_mov_b32 m0, s14
	s_add_i32 s16, s16, 0x1e000
	global_load_lds_dwordx4 v[4:5], off
	v_lshl_add_u64 v[2:3], s[8:9], 0, v[2:3]
	s_mov_b32 m0, s15
	s_and_b64 vcc, exec, s[0:1]
	global_load_lds_dwordx4 v[2:3], off
	v_lshl_add_u64 v[2:3], s[8:9], 0, v[6:7]
	s_mov_b32 m0, s16
	s_nop 0
	global_load_lds_dwordx4 v[2:3], off
	v_lshlrev_b32_e32 v2, 1, v0
	v_and_b32_e32 v2, 32, v2
	v_and_b32_e32 v3, 0x100, v13
	v_and_or_b32 v2, v12, s44, v2
	v_or3_b32 v148, v2, v3, v15
	v_lshlrev_b32_e32 v2, 8, v0
	v_lshlrev_b32_e32 v0, 4, v0
	v_and_b32_e32 v151, 0x1f00, v2
	v_and_b32_e32 v149, 0xf0, v0
	s_cbranch_vccnz .LBB0_542
	s_add_i32 s8, 0, 0x4000
	v_add_u32_e32 v0, s8, v151
	v_xad_u32 v10, v150, v149, v0
	ds_read_b128 v[2:5], v10 offset:0
	ds_read_b128 v[6:9], v10 offset:0x2000
	v_or_b32_e32 v10, 32, v150
	v_xad_u32 v10, v10, v149, v0
	ds_read_b128 v[34:37], v10 offset:0
	ds_read_b128 v[38:41], v10 offset:0x2000
	v_or_b32_e32 v10, 64, v150
	v_xad_u32 v10, v10, v149, v0
	ds_read_b128 v[42:45], v10 offset:0
	ds_read_b128 v[46:49], v10 offset:0x2000
	v_or_b32_e32 v10, 0x60, v150
	v_xad_u32 v10, v10, v149, v0
	ds_read_b128 v[50:53], v10 offset:0
	ds_read_b128 v[54:57], v10 offset:0x2000
	s_waitcnt lgkmcnt(0)
	v_mfma_f32_32x32x16_bf16 v[18:33], v[2:5], v[140:143], 0
	v_mfma_f32_32x32x16_bf16 v[2:17], v[6:9], v[140:143], 0
	v_mfma_f32_32x32x16_bf16 v[18:33], v[34:37], v[136:139], v[18:33]
	v_or_b32_e32 v34, 0x80, v150
	v_mfma_f32_32x32x16_bf16 v[2:17], v[38:41], v[136:139], v[2:17]
	v_mfma_f32_32x32x16_bf16 v[18:33], v[42:45], v[132:135], v[18:33]
	v_xad_u32 v42, v34, v149, v0
	ds_read_b128 v[34:37], v42 offset:0
	ds_read_b128 v[38:41], v42 offset:0x2000
	v_or_b32_e32 v42, 0xa0, v150
	v_mfma_f32_32x32x16_bf16 v[2:17], v[46:49], v[132:135], v[2:17]
	v_mfma_f32_32x32x16_bf16 v[18:33], v[50:53], v[128:131], v[18:33]
	v_xad_u32 v50, v42, v149, v0
	ds_read_b128 v[42:45], v50 offset:0
	ds_read_b128 v[46:49], v50 offset:0x2000
	v_or_b32_e32 v50, 0xc0, v150
	v_xad_u32 v58, v50, v149, v0
	ds_read_b128 v[50:53], v58 offset:0
	v_mfma_f32_32x32x16_bf16 v[2:17], v[54:57], v[128:131], v[2:17]
	ds_read_b128 v[54:57], v58 offset:0x2000
	v_or_b32_e32 v58, 0xe0, v150
	v_xad_u32 v0, v58, v149, v0
	ds_read_b128 v[58:61], v0 offset:0
	ds_read_b128 v[62:65], v0 offset:0x2000
	s_waitcnt lgkmcnt(0)
	v_mfma_f32_32x32x16_bf16 v[18:33], v[34:37], v[124:127], v[18:33]
	v_add_u32_e32 v0, 0, v148
	v_mfma_f32_32x32x16_bf16 v[18:33], v[42:45], v[120:123], v[18:33]
	v_mfma_f32_32x32x16_bf16 v[2:17], v[38:41], v[124:127], v[2:17]
	v_mfma_f32_32x32x16_bf16 v[18:33], v[50:53], v[116:119], v[18:33]
	v_mfma_f32_32x32x16_bf16 v[2:17], v[46:49], v[120:123], v[2:17]
	v_mfma_f32_32x32x16_bf16 v[18:33], v[58:61], v[112:115], v[18:33]
	v_mfma_f32_32x32x16_bf16 v[2:17], v[54:57], v[116:119], v[2:17]
	s_nop 10
	v_max_f32_e32 v34, v19, v19
	v_max_f32_e32 v35, v18, v18
	v_max_f32_e32 v34, v35, v34
	v_max3_f32 v34, v34, v20, v21
	v_max3_f32 v34, v34, v22, v23
	v_max3_f32 v34, v34, v24, v25
	v_max3_f32 v34, v34, v26, v27
	v_mfma_f32_32x32x16_bf16 v[2:17], v[62:65], v[112:115], v[2:17]
	v_max3_f32 v34, v34, v28, v29
	v_max3_f32 v34, v34, v30, v31
	v_max3_f32 v34, v34, v32, v33
	s_nop 8
	v_max3_f32 v34, v34, v2, v3
	v_max3_f32 v34, v34, v4, v5
	v_max3_f32 v34, v34, v6, v7
	v_max3_f32 v34, v34, v8, v9
	v_max3_f32 v34, v34, v10, v11
	v_max3_f32 v34, v34, v12, v13
	v_max3_f32 v34, v34, v14, v15
	v_max3_f32 v34, v34, v16, v17
	v_mov_b32_e32 v35, v34
	s_nop 1
	v_permlane32_swap_b32_e32 v34, v35
	v_max_f32_e32 v35, v35, v35
	v_max_f32_e32 v34, v34, v34
	v_max_f32_e32 v34, v34, v35
	v_add_f32_e32 v35, 0x7149f2ca, v34
	v_cmp_ge_f32_e32 vcc, s45, v35
	s_cmp_eq_u64 vcc, exec
	v_max_f32_e32 v34, 0xf149f2ca, v34
	s_cselect_b64 vcc, -1, 0
	v_sub_f32_e32 v35, 0xf149f2ca, v34
	v_cndmask_b32_e32 v152, v34, v214, vcc
	v_mul_f32_e32 v34, 0xbe0293ee, v34
	v_cndmask_b32_e32 v34, v34, v215, vcc
	v_fmamk_f32 v2, v2, 0x3e0293ee, v34
	v_exp_f32_e32 v36, v2
	v_fmamk_f32 v2, v3, 0x3e0293ee, v34
	v_exp_f32_e32 v37, v2
	v_fmamk_f32 v2, v4, 0x3e0293ee, v34
	v_exp_f32_e32 v38, v2
	v_fmamk_f32 v2, v5, 0x3e0293ee, v34
	v_exp_f32_e32 v39, v2
	v_fmamk_f32 v2, v6, 0x3e0293ee, v34
	v_exp_f32_e32 v40, v2
	v_fmamk_f32 v2, v7, 0x3e0293ee, v34
	v_exp_f32_e32 v41, v2
	v_fmamk_f32 v2, v8, 0x3e0293ee, v34
	v_exp_f32_e32 v42, v2
	v_fmamk_f32 v2, v9, 0x3e0293ee, v34
	v_exp_f32_e32 v43, v2
	v_fmamk_f32 v2, v10, 0x3e0293ee, v34
	v_exp_f32_e32 v44, v2
	v_fmamk_f32 v2, v11, 0x3e0293ee, v34
	v_fmamk_f32 v18, v18, 0x3e0293ee, v34
	v_exp_f32_e32 v45, v2
	v_fmamk_f32 v2, v12, 0x3e0293ee, v34
	v_exp_f32_e32 v18, v18
	v_fmamk_f32 v19, v19, 0x3e0293ee, v34
	v_exp_f32_e32 v46, v2
	v_fmamk_f32 v2, v13, 0x3e0293ee, v34
	v_exp_f32_e32 v19, v19
	v_fmamk_f32 v20, v20, 0x3e0293ee, v34
	v_exp_f32_e32 v47, v2
	v_fmamk_f32 v2, v14, 0x3e0293ee, v34
	v_exp_f32_e32 v20, v20
	v_fmamk_f32 v21, v21, 0x3e0293ee, v34
	v_exp_f32_e32 v14, v2
	v_fmamk_f32 v2, v15, 0x3e0293ee, v34
	v_exp_f32_e32 v21, v21
	v_fmamk_f32 v22, v22, 0x3e0293ee, v34
	v_exp_f32_e32 v15, v2
	v_fmamk_f32 v2, v16, 0x3e0293ee, v34
	v_exp_f32_e32 v22, v22
	v_fmamk_f32 v23, v23, 0x3e0293ee, v34
	v_exp_f32_e32 v16, v2
	v_add_f32_e32 v2, 0, v18
	v_exp_f32_e32 v23, v23
	v_fmamk_f32 v24, v24, 0x3e0293ee, v34
	v_add_f32_e32 v2, v19, v2
	v_exp_f32_e32 v24, v24
	v_fmamk_f32 v25, v25, 0x3e0293ee, v34
	v_add_f32_e32 v2, v20, v2
	v_exp_f32_e32 v25, v25
	v_fmamk_f32 v26, v26, 0x3e0293ee, v34
	v_add_f32_e32 v2, v21, v2
	v_exp_f32_e32 v26, v26
	v_fmamk_f32 v27, v27, 0x3e0293ee, v34
	v_add_f32_e32 v2, v22, v2
	v_exp_f32_e32 v27, v27
	v_fmamk_f32 v28, v28, 0x3e0293ee, v34
	v_add_f32_e32 v2, v23, v2
	v_exp_f32_e32 v28, v28
	v_fmamk_f32 v29, v29, 0x3e0293ee, v34
	v_add_f32_e32 v2, v24, v2
	v_exp_f32_e32 v29, v29
	v_fmamk_f32 v30, v30, 0x3e0293ee, v34
	v_add_f32_e32 v2, v25, v2
	v_exp_f32_e32 v30, v30
	v_fmamk_f32 v31, v31, 0x3e0293ee, v34
	v_add_f32_e32 v2, v26, v2
	v_exp_f32_e32 v31, v31
	v_fmamk_f32 v32, v32, 0x3e0293ee, v34
	v_add_f32_e32 v2, v27, v2
	v_exp_f32_e32 v32, v32
	v_fmamk_f32 v33, v33, 0x3e0293ee, v34
	v_add_f32_e32 v2, v28, v2
	v_exp_f32_e32 v33, v33
	v_add_f32_e32 v2, v29, v2
	v_add_f32_e32 v2, v30, v2
	v_add_f32_e32 v2, v31, v2
	v_add_f32_e32 v2, v32, v2
	v_add_f32_e32 v2, v33, v2
	v_add_f32_e32 v2, v36, v2
	v_add_f32_e32 v2, v37, v2
	v_add_f32_e32 v2, v38, v2
	v_add_f32_e32 v2, v39, v2
	v_add_f32_e32 v2, v40, v2
	v_add_f32_e32 v2, v41, v2
	v_add_f32_e32 v2, v42, v2
	v_add_f32_e32 v2, v43, v2
	v_add_f32_e32 v2, v44, v2
	v_add_f32_e32 v2, v45, v2
	v_fmac_f32_e32 v34, 0x3e0293ee, v17
	v_add_f32_e32 v2, v46, v2
	v_exp_f32_e32 v17, v34
	v_add_f32_e32 v2, v47, v2
	v_add_f32_e32 v2, v14, v2
	v_mul_f32_e32 v35, 0x3e0293ee, v35
	v_add_f32_e32 v2, v15, v2
	v_exp_f32_e32 v35, v35
	v_add_f32_e32 v2, v16, v2
	v_add_f32_e32 v2, v17, v2
	v_mov_b32_e32 v3, v2
	s_nop 1
	v_permlane32_swap_b32_e32 v2, v3
	v_cndmask_b32_e64 v35, v35, 1.0, vcc
	v_add_f32_e32 v153, v2, v3
	v_mul_f32_e32 v34, 0, v35
	v_fmac_f32_e32 v153, 0, v35
	v_cvt_pk_bf16_f32 v2, v18, v19
	v_cvt_pk_bf16_f32 v3, v20, v21
	v_cvt_pk_bf16_f32 v4, v22, v23
	v_cvt_pk_bf16_f32 v5, v24, v25
	v_cvt_pk_bf16_f32 v6, v26, v27
	v_cvt_pk_bf16_f32 v7, v28, v29
	v_cvt_pk_bf16_f32 v8, v30, v31
	v_cvt_pk_bf16_f32 v9, v32, v33
	v_cvt_pk_bf16_f32 v10, v36, v37
	v_cvt_pk_bf16_f32 v11, v38, v39
	v_cvt_pk_bf16_f32 v12, v40, v41
	v_cvt_pk_bf16_f32 v13, v42, v43
	v_cvt_pk_bf16_f32 v80, v44, v45
	v_cvt_pk_bf16_f32 v81, v46, v47
	v_cvt_pk_bf16_f32 v82, v14, v15
	v_cvt_pk_bf16_f32 v83, v16, v17
	s_nop 0
	v_permlane32_swap_b32_e32 v2, v4
	v_permlane32_swap_b32_e32 v3, v5
	v_permlane32_swap_b32_e32 v6, v8
	v_permlane32_swap_b32_e32 v7, v9
	v_permlane32_swap_b32_e32 v10, v12
	v_permlane32_swap_b32_e32 v11, v13
	v_permlane32_swap_b32_e32 v80, v82
	v_permlane32_swap_b32_e32 v81, v83
	v_cmp_gt_f32_e32 vcc, 1.0, v35
	s_cmp_lg_u64 vcc, 0
	s_cselect_b64 vcc, -1, 0
	ds_read_b64_tr_b16 v[32:33], v0 offset:0
	v_cndmask_b32_e32 v16, 0, v34, vcc
	ds_read_b64_tr_b16 v[34:35], v0 offset:0x800
	ds_read_b64_tr_b16 v[36:37], v0 offset:0x1000
	ds_read_b64_tr_b16 v[38:39], v0 offset:0x1800
	ds_read_b64_tr_b16 v[40:41], v0 offset:0x2000
	ds_read_b64_tr_b16 v[42:43], v0 offset:0x2800
	ds_read_b64_tr_b16 v[44:45], v0 offset:0x3000
	ds_read_b64_tr_b16 v[46:47], v0 offset:0x3800
	s_waitcnt lgkmcnt(0)
	v_mov_b32_e32 v17, v16
	v_mov_b32_e32 v18, v16
	v_mov_b32_e32 v19, v16
	v_mov_b32_e32 v20, v16
	v_mov_b32_e32 v21, v16
	v_mov_b32_e32 v22, v16
	v_mov_b32_e32 v23, v16
	v_mov_b32_e32 v24, v16
	v_mov_b32_e32 v25, v16
	v_mov_b32_e32 v26, v16
	v_mov_b32_e32 v27, v16
	v_mov_b32_e32 v28, v16
	v_mov_b32_e32 v29, v16
	v_mov_b32_e32 v30, v16
	v_mov_b32_e32 v31, v16
	s_nop 1
	v_mfma_f32_32x32x16_bf16 v[64:79], v[32:35], v[2:5], v[16:31]
	ds_read_b64_tr_b16 v[32:33], v0 offset:0x200
	ds_read_b64_tr_b16 v[34:35], v0 offset:0xa00
	v_mfma_f32_32x32x16_bf16 v[64:79], v[36:39], v[6:9], v[64:79]
	ds_read_b64_tr_b16 v[36:37], v0 offset:0x1200
	ds_read_b64_tr_b16 v[38:39], v0 offset:0x1a00
	v_mfma_f32_32x32x16_bf16 v[64:79], v[40:43], v[10:13], v[64:79]
	ds_read_b64_tr_b16 v[40:41], v0 offset:0x2200
	ds_read_b64_tr_b16 v[42:43], v0 offset:0x2a00
	v_mfma_f32_32x32x16_bf16 v[64:79], v[44:47], v[80:83], v[64:79]
	ds_read_b64_tr_b16 v[44:45], v0 offset:0x3200
	ds_read_b64_tr_b16 v[46:47], v0 offset:0x3a00
	s_waitcnt lgkmcnt(0)
	v_mfma_f32_32x32x16_bf16 v[48:63], v[32:35], v[2:5], v[16:31]
	ds_read_b64_tr_b16 v[84:85], v0 offset:0x400
	ds_read_b64_tr_b16 v[86:87], v0 offset:0xc00
	ds_read_b64_tr_b16 v[88:89], v0 offset:0x1400
	ds_read_b64_tr_b16 v[90:91], v0 offset:0x1c00
	ds_read_b64_tr_b16 v[92:93], v0 offset:0x2400
	ds_read_b64_tr_b16 v[94:95], v0 offset:0x2c00
	ds_read_b64_tr_b16 v[96:97], v0 offset:0x3400
	v_mfma_f32_32x32x16_bf16 v[48:63], v[36:39], v[6:9], v[48:63]
	ds_read_b64_tr_b16 v[98:99], v0 offset:0x3c00
	s_waitcnt lgkmcnt(0)
	v_mfma_f32_32x32x16_bf16 v[48:63], v[40:43], v[10:13], v[48:63]
	v_mfma_f32_32x32x16_bf16 v[48:63], v[44:47], v[80:83], v[48:63]
	v_mfma_f32_32x32x16_bf16 v[32:47], v[84:87], v[2:5], v[16:31]
	ds_read_b64_tr_b16 v[84:85], v0 offset:0x600
	ds_read_b64_tr_b16 v[86:87], v0 offset:0xe00
	v_mfma_f32_32x32x16_bf16 v[32:47], v[88:91], v[6:9], v[32:47]
	ds_read_b64_tr_b16 v[88:89], v0 offset:0x1600
	ds_read_b64_tr_b16 v[90:91], v0 offset:0x1e00
	v_mfma_f32_32x32x16_bf16 v[32:47], v[92:95], v[10:13], v[32:47]
	ds_read_b64_tr_b16 v[92:93], v0 offset:0x2600
	ds_read_b64_tr_b16 v[94:95], v0 offset:0x2e00
	v_mfma_f32_32x32x16_bf16 v[32:47], v[96:99], v[80:83], v[32:47]
	ds_read_b64_tr_b16 v[96:97], v0 offset:0x3600
	ds_read_b64_tr_b16 v[98:99], v0 offset:0x3e00
	s_waitcnt lgkmcnt(0)
	v_mfma_f32_32x32x16_bf16 v[16:31], v[84:87], v[2:5], v[16:31]
	v_mfma_f32_32x32x16_bf16 v[16:31], v[88:91], v[6:9], v[16:31]
	v_mfma_f32_32x32x16_bf16 v[16:31], v[92:95], v[10:13], v[16:31]
	v_mfma_f32_32x32x16_bf16 v[16:31], v[96:99], v[80:83], v[16:31]
	s_branch .LBB0_543

.LBB0_1377:
	v_mov_b64_e32 v[0:1], s[76:77]
	v_mad_u64_u32 v[0:1], s[18:19], v128, s88, v[0:1]
	v_mov_b32_e32 v2, v1
	v_mad_u64_u32 v[2:3], s[18:19], v129, s88, v[2:3]
	v_mov_b32_e32 v1, v2
	s_lshl_b32 s38, s20, 1
	v_lshl_add_u64 v[130:131], v[0:1], 0, s[38:39]
	v_lshl_add_u64 v[0:1], v[130:131], 0, v[160:161]
	v_mov_b32_e32 v10, v180
	global_load_dwordx4 v[124:127], v[0:1], off offset:2048
	global_load_dwordx4 v[120:123], v[0:1], off offset:2080
	global_load_dwordx4 v[116:119], v[0:1], off offset:2112
	global_load_dwordx4 v[112:115], v[0:1], off offset:2144
	global_load_dwordx4 v[108:111], v[0:1], off offset:2176
	global_load_dwordx4 v[104:107], v[0:1], off offset:2208
	global_load_dwordx4 v[100:103], v[0:1], off offset:2240
	global_load_dwordx4 v[96:99], v[0:1], off offset:2272
	v_readfirstlane_b32 s15, v10
	s_lshl_b32 s15, s15, 4
	s_and_b32 s15, s15, 0xfffffc00
	v_and_b32_e32 v0, 63, v10
	s_ashr_i32 s18, s15, 8
	v_lshlrev_b32_e32 v11, 4, v0
	s_and_b32 s19, s18, 0xfffff0
	s_lshr_b32 s18, s18, 1
	v_lshlrev_b32_e32 v12, 3, v0
	v_bfe_u32 v0, v10, 2, 2
	v_lshrrev_b32_e32 v13, 1, v10
	v_or_b32_e32 v2, s15, v11
	s_and_b32 s18, s18, 4
	v_and_or_b32 v6, v13, 8, v0
	v_ashrrev_i32_e32 v0, 8, v2
	s_or_b32 s18, s19, s18
	v_xor_b32_e32 v3, v0, v10
	v_or_b32_e32 v4, s18, v6
	s_add_i32 s18, s15, 0x2000
	v_mul_hi_i32_i24_e32 v1, s14, v0
	v_mul_i32_i24_e32 v0, s14, v0
	v_lshlrev_b32_e32 v3, 3, v3
	v_lshrrev_b32_e32 v2, 4, v2
	v_or_b32_e32 v7, s18, v11
	s_ashr_i32 s18, s18, 8
	v_and_b32_e32 v14, 24, v12
	v_and_or_b32 v0, v3, s40, v0
	v_and_b32_e32 v2, 0x60, v2
	v_mul_hi_i32_i24_e32 v3, s14, v4
	v_mul_i32_i24_e32 v4, s14, v4
	s_and_b32 s19, s18, 0xfffff0
	s_lshr_b32 s18, s18, 1
	v_or3_b32 v2, v2, v14, v4
	v_ashrrev_i32_e32 v4, 8, v7
	s_and_b32 s18, s18, 4
	v_xor_b32_e32 v8, v4, v10
	s_or_b32 s18, s19, s18
	v_mul_hi_i32_i24_e32 v5, s14, v4
	v_mul_i32_i24_e32 v4, s14, v4
	v_lshlrev_b32_e32 v8, 3, v8
	v_or_b32_e32 v6, s18, v6
	v_lshrrev_b32_e32 v7, 4, v7
	v_and_or_b32 v4, v8, s40, v4
	v_and_b32_e32 v8, 0x60, v7
	v_mul_hi_i32_i24_e32 v7, s14, v6
	v_mul_i32_i24_e32 v6, s14, v6
	v_or3_b32 v6, v8, v14, v6
	s_add_i32 s15, s15, 0
	v_lshlrev_b64 v[2:3], 1, v[2:3]
	v_lshl_add_u64 v[8:9], s[12:13], 0, v[2:3]
	s_mov_b32 m0, s15
	v_lshlrev_b64 v[6:7], 1, v[6:7]
	global_load_lds_dwordx4 v[8:9], off
	v_lshl_add_u64 v[8:9], s[12:13], 0, v[6:7]
	s_add_i32 m0, s15, 0x2000
	v_lshlrev_b64 v[0:1], 1, v[0:1]
	global_load_lds_dwordx4 v[8:9], off
	v_lshl_add_u64 v[8:9], s[8:9], 0, v[0:1]
	s_add_i32 m0, s15, 0x4000
	v_lshlrev_b64 v[4:5], 1, v[4:5]
	global_load_lds_dwordx4 v[8:9], off
	s_add_i32 m0, s15, 0x6000
	s_lshl_b32 s14, s14, 7
	v_lshl_add_u64 v[8:9], s[8:9], 0, v[4:5]
	s_add_u32 s8, s8, s14
	s_addc_u32 s9, s9, 0
	s_add_u32 s12, s12, s14
	s_addc_u32 s13, s13, 0
	global_load_lds_dwordx4 v[8:9], off
	s_add_i32 m0, s15, 0x8000
	v_lshl_add_u64 v[8:9], s[12:13], 0, v[2:3]
	global_load_lds_dwordx4 v[8:9], off
	v_lshl_add_u64 v[8:9], s[12:13], 0, v[6:7]
	s_add_i32 m0, s15, 0xa000
	v_and_b32_e32 v135, 16, v13
	global_load_lds_dwordx4 v[8:9], off
	v_lshl_add_u64 v[8:9], s[8:9], 0, v[0:1]
	s_add_i32 m0, s15, 0xc000
	s_nop 0
	global_load_lds_dwordx4 v[8:9], off
	s_add_i32 m0, s15, 0xe000
	v_lshl_add_u64 v[8:9], s[8:9], 0, v[4:5]
	s_add_u32 s8, s8, s14
	s_addc_u32 s9, s9, 0
	s_add_u32 s12, s12, s14
	s_addc_u32 s13, s13, 0
	global_load_lds_dwordx4 v[8:9], off
	s_add_i32 m0, s15, 0x10000
	v_lshl_add_u64 v[8:9], s[12:13], 0, v[2:3]
	global_load_lds_dwordx4 v[8:9], off
	v_lshl_add_u64 v[8:9], s[12:13], 0, v[6:7]
	s_add_i32 m0, s15, 0x12000
	s_nop 0
	global_load_lds_dwordx4 v[8:9], off
	v_lshl_add_u64 v[8:9], s[8:9], 0, v[0:1]
	s_add_i32 m0, s15, 0x14000
	s_nop 0
	global_load_lds_dwordx4 v[8:9], off
	s_add_i32 m0, s15, 0x16000
	v_lshl_add_u64 v[8:9], s[8:9], 0, v[4:5]
	s_add_u32 s8, s8, s14
	s_addc_u32 s9, s9, 0
	s_add_u32 s12, s12, s14
	global_load_lds_dwordx4 v[8:9], off
	s_addc_u32 s13, s13, 0
	s_add_i32 m0, s15, 0x18000
	s_add_i32 s14, s15, 0x1a000
	s_waitcnt vmcnt(8)
	s_barrier
	v_lshl_add_u64 v[2:3], s[12:13], 0, v[2:3]
	s_add_i32 s18, s15, 0x1c000
	global_load_lds_dwordx4 v[2:3], off
	v_lshl_add_u64 v[2:3], s[12:13], 0, v[6:7]
	s_mov_b32 m0, s14
	s_add_i32 s15, s15, 0x1e000
	global_load_lds_dwordx4 v[2:3], off
	v_lshl_add_u64 v[0:1], s[8:9], 0, v[0:1]
	s_mov_b32 m0, s18
	s_and_b64 vcc, exec, s[0:1]
	global_load_lds_dwordx4 v[0:1], off
	v_lshl_add_u64 v[0:1], s[8:9], 0, v[4:5]
	s_mov_b32 m0, s15
	s_movk_i32 s8, 0xc0
	global_load_lds_dwordx4 v[0:1], off
	v_lshlrev_b32_e32 v0, 1, v10
	v_and_b32_e32 v0, 32, v0
	v_and_b32_e32 v1, 0x100, v12
	v_and_or_b32 v0, v11, s8, v0
	v_or3_b32 v133, v0, v1, v14
	v_lshlrev_b32_e32 v0, 8, v10
	v_and_b32_e32 v136, 0x1f00, v0
	v_lshlrev_b32_e32 v0, 4, v10
	v_and_b32_e32 v134, 0xf0, v0
	s_cbranch_vccnz .LBB0_1380
	s_add_i32 s8, 0, 0x4000
	v_add_u32_e32 v60, s8, v136
	v_xad_u32 v8, v135, v134, v60
	ds_read_b128 v[0:3], v8 offset:0
	ds_read_b128 v[4:7], v8 offset:0x2000
	v_or_b32_e32 v8, 32, v135
	v_xad_u32 v8, v8, v134, v60
	ds_read_b128 v[32:35], v8 offset:0
	ds_read_b128 v[36:39], v8 offset:0x2000
	v_or_b32_e32 v8, 64, v135
	v_xad_u32 v8, v8, v134, v60
	ds_read_b128 v[40:43], v8 offset:0
	ds_read_b128 v[44:47], v8 offset:0x2000
	v_or_b32_e32 v8, 0x60, v135
	v_xad_u32 v8, v8, v134, v60
	ds_read_b128 v[48:51], v8 offset:0
	ds_read_b128 v[52:55], v8 offset:0x2000
	s_waitcnt lgkmcnt(0)
	v_mfma_f32_32x32x16_bf16 v[16:31], v[0:3], v[124:127], 0
	v_mfma_f32_32x32x16_bf16 v[0:15], v[4:7], v[124:127], 0
	v_mfma_f32_32x32x16_bf16 v[16:31], v[32:35], v[120:123], v[16:31]
	v_or_b32_e32 v32, 0x80, v135
	v_mfma_f32_32x32x16_bf16 v[0:15], v[36:39], v[120:123], v[0:15]
	v_mfma_f32_32x32x16_bf16 v[16:31], v[40:43], v[116:119], v[16:31]
	v_xad_u32 v40, v32, v134, v60
	ds_read_b128 v[32:35], v40 offset:0
	ds_read_b128 v[36:39], v40 offset:0x2000
	v_or_b32_e32 v40, 0xa0, v135
	v_xad_u32 v56, v40, v134, v60
	ds_read_b128 v[40:43], v56 offset:0
	v_mfma_f32_32x32x16_bf16 v[0:15], v[44:47], v[116:119], v[0:15]
	ds_read_b128 v[44:47], v56 offset:0x2000
	v_or_b32_e32 v56, 0xc0, v135
	v_xad_u32 v61, v56, v134, v60
	v_mfma_f32_32x32x16_bf16 v[16:31], v[48:51], v[112:115], v[16:31]
	ds_read_b128 v[48:51], v61 offset:0
	ds_read_b128 v[56:59], v61 offset:0x2000
	v_or_b32_e32 v61, 0xe0, v135
	v_xad_u32 v68, v61, v134, v60
	ds_read_b128 v[60:63], v68 offset:0
	ds_read_b128 v[64:67], v68 offset:0x2000
	s_waitcnt lgkmcnt(0)
	v_mfma_f32_32x32x16_bf16 v[0:15], v[52:55], v[112:115], v[0:15]
	v_mfma_f32_32x32x16_bf16 v[16:31], v[32:35], v[108:111], v[16:31]
	v_add_u32_e32 v132, 0, v133
	v_mfma_f32_32x32x16_bf16 v[16:31], v[40:43], v[104:107], v[16:31]
	v_mfma_f32_32x32x16_bf16 v[0:15], v[36:39], v[108:111], v[0:15]
	v_mfma_f32_32x32x16_bf16 v[16:31], v[48:51], v[100:103], v[16:31]
	v_mfma_f32_32x32x16_bf16 v[0:15], v[44:47], v[104:107], v[0:15]
	v_mfma_f32_32x32x16_bf16 v[16:31], v[60:63], v[96:99], v[16:31]
	v_mfma_f32_32x32x16_bf16 v[0:15], v[56:59], v[100:103], v[0:15]
	s_nop 10
	v_max_f32_e32 v32, v17, v17
	v_max_f32_e32 v33, v16, v16
	v_max_f32_e32 v32, v33, v32
	v_max3_f32 v32, v32, v18, v19
	v_max3_f32 v32, v32, v20, v21
	v_max3_f32 v32, v32, v22, v23
	v_max3_f32 v32, v32, v24, v25
	v_mfma_f32_32x32x16_bf16 v[0:15], v[64:67], v[96:99], v[0:15]
	v_max3_f32 v32, v32, v26, v27
	v_max3_f32 v32, v32, v28, v29
	v_max3_f32 v32, v32, v30, v31
	s_nop 8
	v_max3_f32 v32, v32, v0, v1
	v_max3_f32 v32, v32, v2, v3
	v_max3_f32 v32, v32, v4, v5
	v_max3_f32 v32, v32, v6, v7
	v_max3_f32 v32, v32, v8, v9
	v_max3_f32 v32, v32, v10, v11
	v_max3_f32 v32, v32, v12, v13
	v_max3_f32 v32, v32, v14, v15
	v_mov_b32_e32 v33, v32
	s_nop 1
	v_permlane32_swap_b32_e32 v32, v33
	v_max_f32_e32 v33, v33, v33
	v_max_f32_e32 v32, v32, v32
	v_max_f32_e32 v32, v32, v33
	v_add_f32_e32 v33, 0x7149f2ca, v32
	v_cmp_ge_f32_e32 vcc, s46, v33
	s_cmp_eq_u64 vcc, exec
	v_max_f32_e32 v32, 0xf149f2ca, v32
	s_cselect_b64 vcc, -1, 0
	v_sub_f32_e32 v33, 0xf149f2ca, v32
	v_cndmask_b32_e32 v138, v32, v172, vcc
	v_mul_f32_e32 v32, 0xbe0293ee, v32
	v_cndmask_b32_e32 v32, v32, v173, vcc
	v_fmamk_f32 v16, v16, 0x3e0293ee, v32
	v_exp_f32_e32 v16, v16
	v_fmamk_f32 v17, v17, 0x3e0293ee, v32
	v_exp_f32_e32 v17, v17
	v_fmamk_f32 v18, v18, 0x3e0293ee, v32
	v_exp_f32_e32 v18, v18
	v_fmamk_f32 v19, v19, 0x3e0293ee, v32
	v_exp_f32_e32 v19, v19
	v_fmamk_f32 v20, v20, 0x3e0293ee, v32
	v_fmamk_f32 v21, v21, 0x3e0293ee, v32
	v_fmamk_f32 v22, v22, 0x3e0293ee, v32
	v_fmamk_f32 v23, v23, 0x3e0293ee, v32
	v_fmamk_f32 v24, v24, 0x3e0293ee, v32
	v_fmamk_f32 v25, v25, 0x3e0293ee, v32
	v_fmamk_f32 v26, v26, 0x3e0293ee, v32
	v_fmamk_f32 v27, v27, 0x3e0293ee, v32
	v_fmamk_f32 v28, v28, 0x3e0293ee, v32
	v_fmamk_f32 v29, v29, 0x3e0293ee, v32
	v_fmamk_f32 v30, v30, 0x3e0293ee, v32
	v_fmamk_f32 v31, v31, 0x3e0293ee, v32
	v_fmamk_f32 v0, v0, 0x3e0293ee, v32
	v_fmamk_f32 v1, v1, 0x3e0293ee, v32
	v_fmamk_f32 v2, v2, 0x3e0293ee, v32
	v_fmamk_f32 v3, v3, 0x3e0293ee, v32
	v_fmamk_f32 v4, v4, 0x3e0293ee, v32
	v_fmamk_f32 v5, v5, 0x3e0293ee, v32
	v_fmamk_f32 v6, v6, 0x3e0293ee, v32
	v_fmamk_f32 v7, v7, 0x3e0293ee, v32
	v_fmamk_f32 v8, v8, 0x3e0293ee, v32
	v_fmamk_f32 v9, v9, 0x3e0293ee, v32
	v_fmamk_f32 v10, v10, 0x3e0293ee, v32
	v_fmamk_f32 v11, v11, 0x3e0293ee, v32
	v_fmamk_f32 v12, v12, 0x3e0293ee, v32
	v_fmamk_f32 v13, v13, 0x3e0293ee, v32
	v_fmamk_f32 v14, v14, 0x3e0293ee, v32
	v_fmac_f32_e32 v32, 0x3e0293ee, v15
	v_exp_f32_e32 v20, v20
	v_exp_f32_e32 v15, v32
	v_add_f32_e32 v32, 0, v16
	v_exp_f32_e32 v21, v21
	v_add_f32_e32 v32, v17, v32
	v_exp_f32_e32 v22, v22
	v_add_f32_e32 v32, v18, v32
	v_exp_f32_e32 v23, v23
	v_add_f32_e32 v32, v19, v32
	v_exp_f32_e32 v24, v24
	v_add_f32_e32 v32, v20, v32
	v_exp_f32_e32 v25, v25
	v_add_f32_e32 v32, v21, v32
	v_exp_f32_e32 v26, v26
	v_add_f32_e32 v32, v22, v32
	v_exp_f32_e32 v27, v27
	v_add_f32_e32 v32, v23, v32
	v_exp_f32_e32 v28, v28
	v_add_f32_e32 v32, v24, v32
	v_exp_f32_e32 v29, v29
	v_add_f32_e32 v32, v25, v32
	v_exp_f32_e32 v30, v30
	v_add_f32_e32 v32, v26, v32
	v_exp_f32_e32 v31, v31
	v_add_f32_e32 v32, v27, v32
	v_exp_f32_e32 v0, v0
	v_add_f32_e32 v32, v28, v32
	v_exp_f32_e32 v1, v1
	v_add_f32_e32 v32, v29, v32
	v_exp_f32_e32 v2, v2
	v_add_f32_e32 v32, v30, v32
	v_exp_f32_e32 v3, v3
	v_add_f32_e32 v32, v31, v32
	v_exp_f32_e32 v4, v4
	v_add_f32_e32 v32, v0, v32
	v_exp_f32_e32 v5, v5
	v_add_f32_e32 v32, v1, v32
	v_exp_f32_e32 v6, v6
	v_add_f32_e32 v32, v2, v32
	v_exp_f32_e32 v7, v7
	v_add_f32_e32 v32, v3, v32
	v_exp_f32_e32 v8, v8
	v_add_f32_e32 v32, v4, v32
	v_exp_f32_e32 v9, v9
	v_add_f32_e32 v32, v5, v32
	v_exp_f32_e32 v10, v10
	v_add_f32_e32 v32, v6, v32
	v_exp_f32_e32 v11, v11
	v_add_f32_e32 v32, v7, v32
	v_exp_f32_e32 v12, v12
	v_add_f32_e32 v32, v8, v32
	v_exp_f32_e32 v13, v13
	v_add_f32_e32 v32, v9, v32
	v_exp_f32_e32 v14, v14
	v_add_f32_e32 v32, v10, v32
	v_add_f32_e32 v32, v11, v32
	v_add_f32_e32 v32, v12, v32
	v_mul_f32_e32 v33, 0x3e0293ee, v33
	v_add_f32_e32 v32, v13, v32
	v_exp_f32_e32 v33, v33
	v_add_f32_e32 v32, v14, v32
	v_add_f32_e32 v32, v15, v32
	v_mov_b32_e32 v34, v32
	s_nop 1
	v_permlane32_swap_b32_e32 v32, v34
	v_cndmask_b32_e64 v33, v33, 1.0, vcc
	v_add_f32_e32 v137, v32, v34
	v_mul_f32_e32 v32, 0, v33
	v_fmac_f32_e32 v137, 0, v33
	v_cvt_pk_bf16_f32 v64, v16, v17
	v_cvt_pk_bf16_f32 v65, v18, v19
	v_cvt_pk_bf16_f32 v66, v20, v21
	v_cvt_pk_bf16_f32 v67, v22, v23
	v_cvt_pk_bf16_f32 v68, v24, v25
	v_cvt_pk_bf16_f32 v69, v26, v27
	v_cvt_pk_bf16_f32 v70, v28, v29
	v_cvt_pk_bf16_f32 v71, v30, v31
	v_cvt_pk_bf16_f32 v72, v0, v1
	v_cvt_pk_bf16_f32 v73, v2, v3
	v_cvt_pk_bf16_f32 v74, v4, v5
	v_cvt_pk_bf16_f32 v75, v6, v7
	v_cvt_pk_bf16_f32 v76, v8, v9
	v_cvt_pk_bf16_f32 v77, v10, v11
	v_cvt_pk_bf16_f32 v78, v12, v13
	v_cvt_pk_bf16_f32 v79, v14, v15
	s_nop 0
	v_permlane32_swap_b32_e32 v64, v66
	v_permlane32_swap_b32_e32 v65, v67
	v_permlane32_swap_b32_e32 v68, v70
	v_permlane32_swap_b32_e32 v69, v71
	v_permlane32_swap_b32_e32 v72, v74
	v_permlane32_swap_b32_e32 v73, v75
	v_permlane32_swap_b32_e32 v76, v78
	v_permlane32_swap_b32_e32 v77, v79
	ds_read_b64_tr_b16 v[16:17], v132 offset:0
	ds_read_b64_tr_b16 v[18:19], v132 offset:0x800
	ds_read_b64_tr_b16 v[20:21], v132 offset:0x1000
	ds_read_b64_tr_b16 v[22:23], v132 offset:0x1800
	ds_read_b64_tr_b16 v[24:25], v132 offset:0x2000
	ds_read_b64_tr_b16 v[26:27], v132 offset:0x2800
	v_cmp_gt_f32_e32 vcc, 1.0, v33
	ds_read_b64_tr_b16 v[28:29], v132 offset:0x3000
	s_cmp_lg_u64 vcc, 0
	ds_read_b64_tr_b16 v[30:31], v132 offset:0x3800
	s_cselect_b64 vcc, -1, 0
	s_waitcnt lgkmcnt(0)
	v_cndmask_b32_e32 v0, 0, v32, vcc
	v_mov_b32_e32 v1, v0
	v_mov_b32_e32 v2, v0
	v_mov_b32_e32 v3, v0
	v_mov_b32_e32 v4, v0
	v_mov_b32_e32 v5, v0
	v_mov_b32_e32 v6, v0
	v_mov_b32_e32 v7, v0
	v_mov_b32_e32 v8, v0
	v_mov_b32_e32 v9, v0
	v_mov_b32_e32 v10, v0
	v_mov_b32_e32 v11, v0
	v_mov_b32_e32 v12, v0
	v_mov_b32_e32 v13, v0
	v_mov_b32_e32 v14, v0
	v_mov_b32_e32 v15, v0
	s_nop 1
	v_mfma_f32_32x32x16_bf16 v[48:63], v[16:19], v[64:67], v[0:15]
	ds_read_b64_tr_b16 v[16:17], v132 offset:0x200
	ds_read_b64_tr_b16 v[18:19], v132 offset:0xa00
	v_mfma_f32_32x32x16_bf16 v[48:63], v[20:23], v[68:71], v[48:63]
	ds_read_b64_tr_b16 v[20:21], v132 offset:0x1200
	ds_read_b64_tr_b16 v[22:23], v132 offset:0x1a00
	v_mfma_f32_32x32x16_bf16 v[48:63], v[24:27], v[72:75], v[48:63]
	ds_read_b64_tr_b16 v[24:25], v132 offset:0x2200
	ds_read_b64_tr_b16 v[26:27], v132 offset:0x2a00
	ds_read_b64_tr_b16 v[80:81], v132 offset:0x3200
	ds_read_b64_tr_b16 v[82:83], v132 offset:0x3a00
	s_waitcnt lgkmcnt(0)
	v_mfma_f32_32x32x16_bf16 v[48:63], v[28:31], v[76:79], v[48:63]
	v_mfma_f32_32x32x16_bf16 v[32:47], v[16:19], v[64:67], v[0:15]
	ds_read_b64_tr_b16 v[84:85], v132 offset:0x400
	ds_read_b64_tr_b16 v[86:87], v132 offset:0xc00
	ds_read_b64_tr_b16 v[88:89], v132 offset:0x1400
	ds_read_b64_tr_b16 v[90:91], v132 offset:0x1c00
	ds_read_b64_tr_b16 v[92:93], v132 offset:0x2400
	ds_read_b64_tr_b16 v[94:95], v132 offset:0x2c00
	ds_read_b64_tr_b16 v[140:141], v132 offset:0x3400
	v_mfma_f32_32x32x16_bf16 v[32:47], v[20:23], v[68:71], v[32:47]
	ds_read_b64_tr_b16 v[142:143], v132 offset:0x3c00
	s_waitcnt lgkmcnt(0)
	v_mfma_f32_32x32x16_bf16 v[32:47], v[24:27], v[72:75], v[32:47]
	v_mfma_f32_32x32x16_bf16 v[32:47], v[80:83], v[76:79], v[32:47]
	v_mfma_f32_32x32x16_bf16 v[16:31], v[84:87], v[64:67], v[0:15]
	ds_read_b64_tr_b16 v[80:81], v132 offset:0x600
	ds_read_b64_tr_b16 v[82:83], v132 offset:0xe00
	ds_read_b64_tr_b16 v[84:85], v132 offset:0x1600
	ds_read_b64_tr_b16 v[86:87], v132 offset:0x1e00
	v_mfma_f32_32x32x16_bf16 v[16:31], v[88:91], v[68:71], v[16:31]
	ds_read_b64_tr_b16 v[88:89], v132 offset:0x2600
	ds_read_b64_tr_b16 v[90:91], v132 offset:0x2e00
	v_mfma_f32_32x32x16_bf16 v[16:31], v[92:95], v[72:75], v[16:31]
	ds_read_b64_tr_b16 v[92:93], v132 offset:0x3600
	ds_read_b64_tr_b16 v[94:95], v132 offset:0x3e00
	s_waitcnt lgkmcnt(0)
	v_mfma_f32_32x32x16_bf16 v[16:31], v[140:143], v[76:79], v[16:31]
	v_mfma_f32_32x32x16_bf16 v[0:15], v[80:83], v[64:67], v[0:15]
	v_mfma_f32_32x32x16_bf16 v[0:15], v[84:87], v[68:71], v[0:15]
	v_mfma_f32_32x32x16_bf16 v[0:15], v[88:91], v[72:75], v[0:15]
	v_mfma_f32_32x32x16_bf16 v[0:15], v[92:95], v[76:79], v[0:15]
	s_branch .LBB0_1381
